# DSA loop trims: far-tile bias read once per tile, the never-taken all-unselected step test removed, one nop for the MFMA-VALU distance
# baseline (speedup 1.0000x reference)
; #define LAS __attribute__((address_space(3)))
; __device__ __forceinline__ f32x16 mma32(const h16x8 a, const h16x8 b, const f32x16 c) { return __builtin_amdgcn_mfma_f32_32x32x16_f16(a, b, c, 0, 0, 0); }
; __device__ __forceinline__ void dsa_attn_item(CParams& p, LAS unsigned char* lds, int b, int qb, int tid_in, int wave) {
;     ...
;     for (int kt = 0; kt < nkt; ++kt) {
;         const int k0 = kt * 64; const int cur = kt & 1;
;         const LAS h16* Ks = Ks0 + cur * 8704; const LAS h16* Vt = Vt0 + cur * 9216;
;         const unsigned long long mk = mkn; mkn = bmq[kt + 1 < nkt ? kt + 1 : kt];
;         if (kt + 1 < nkt) ATT_STAGE(cur ^ 1, 2048, 2176, kt + 2);
;         if (__ballot(mk != 0ull) != 0ull) {
;             const bool far = (k0 + 63 + 128 <= q0);
;             const float bfar = bdh[128];
; #pragma unroll
;             for (int sub = 0; sub < 2; ++sub) {
;                 const unsigned mw = (unsigned)(mk >> (32 * sub));
;                 if (__ballot(mw != 0u) == 0ull) continue;
;                 f32x16 sc;
; #pragma unroll
;                 for (int i = 0; i < 16; ++i) sc[i] = 0.f;
; #pragma unroll
;                 for (int s = 0; s < 8; ++s) sc = mma32(*(const LAS h16x8*)(Ks + (32 * sub + r) * 136 + 16 * s + 8 * hh), qf[s], sc);
;                 float mx = -INFINITY;
; #pragma unroll
;                 for (int i = 0; i < 16; ++i) { const int ko = (i & 3) + 8 * (i >> 2) + 4 * hh; const int dist = qp - (k0 + 32 * sub + ko);
;                     float bias = bfar; if (!far) bias = bdh[dist < 0 ? 0 : (dist < 128 ? dist : 128)];
;                     const float v = ((mw >> ko) & 1u) ? sc[i] + bias : -INFINITY; sc[i] = v; mx = fmaxf(mx, v); }
.LBB0_514:
	s_waitcnt vmcnt(2)
	v_cmp_ne_u64_e32 vcc, 0, v[150:151]
	s_cbranch_vccz .LBB0_588
	s_and_b32 s4, s34, 1
	s_mul_i32 s5, s4, 0x4400
	s_mulk_i32 s4, 0x4800
	v_add3_u32 v197, v166, v169, s5
	v_add3_u32 v199, v167, v168, s4
	v_readfirstlane_b32 s6, v145
	ds_read_b32 v200, v184 offset:512
	s_mov_b32 s7, 0x12400
	s_mov_b32 s101, 0
.LdsaA_s0_top:
	v_lshrrev_b32_e32 v214, v146, v150
	v_bfe_u32 v227, v214, 0, 4
	v_lshl_add_u32 v227, v227, 4, s7
	ds_read_b128 v[236:239], v227
	v_bfe_u32 v227, v214, 8, 4
	v_lshl_add_u32 v227, v227, 4, s7
	ds_read_b128 v[240:243], v227
	v_bfe_u32 v227, v214, 16, 4
	v_lshl_add_u32 v227, v227, 4, s7
	ds_read_b128 v[244:247], v227
	v_bfe_u32 v227, v214, 24, 4
	v_lshl_add_u32 v227, v227, 4, s7
	ds_read_b128 v[248:251], v227
	ds_read_b128 v[80:83], v197 offset:0
	ds_read_b128 v[84:87], v197 offset:32
	ds_read_b128 v[88:91], v197 offset:64
	ds_read_b128 v[92:95], v197 offset:96
	ds_read_b128 v[202:205], v197 offset:128
	ds_read_b128 v[206:209], v197 offset:160
	ds_read_b128 v[210:213], v197 offset:192
	ds_read_b128 v[228:231], v197 offset:224
	s_waitcnt lgkmcnt(4)
	v_mfma_f32_32x32x16_f16 v[236:251], v[80:83], v[112:115], v[236:251]
	v_mfma_f32_32x32x16_f16 v[236:251], v[84:87], v[2:5], v[236:251]
	v_mfma_f32_32x32x16_f16 v[236:251], v[88:91], v[6:9], v[236:251]
	v_mfma_f32_32x32x16_f16 v[236:251], v[92:95], v[10:13], v[236:251]
	s_waitcnt lgkmcnt(0)
	v_mfma_f32_32x32x16_f16 v[236:251], v[202:205], v[96:99], v[236:251]
	v_mfma_f32_32x32x16_f16 v[236:251], v[206:209], v[100:103], v[236:251]
	v_mfma_f32_32x32x16_f16 v[236:251], v[210:213], v[104:107], v[236:251]
	v_mfma_f32_32x32x16_f16 v[236:251], v[228:231], v[108:111], v[236:251]
	s_cmp_le_i32 s31, s6
	s_cbranch_scc1 .LdsaA_s0_far
	v_subrev_u32_e32 v202, 0, v196
	v_med3_i32 v202, v202, 0, v226
	v_lshl_add_u32 v202, v202, 2, v184
	ds_read_b32 v202, v202
	v_subrev_u32_e32 v203, 1, v196
	v_med3_i32 v203, v203, 0, v226
	v_lshl_add_u32 v203, v203, 2, v184
	ds_read_b32 v203, v203
	v_subrev_u32_e32 v204, 2, v196
	v_med3_i32 v204, v204, 0, v226
	v_lshl_add_u32 v204, v204, 2, v184
	ds_read_b32 v204, v204
	v_subrev_u32_e32 v205, 3, v196
	v_med3_i32 v205, v205, 0, v226
	v_lshl_add_u32 v205, v205, 2, v184
	ds_read_b32 v205, v205
	v_subrev_u32_e32 v206, 8, v196
	v_med3_i32 v206, v206, 0, v226
	v_lshl_add_u32 v206, v206, 2, v184
	ds_read_b32 v206, v206
	v_subrev_u32_e32 v207, 9, v196
	v_med3_i32 v207, v207, 0, v226
	v_lshl_add_u32 v207, v207, 2, v184
	ds_read_b32 v207, v207
	v_subrev_u32_e32 v208, 10, v196
	v_med3_i32 v208, v208, 0, v226
	v_lshl_add_u32 v208, v208, 2, v184
	ds_read_b32 v208, v208
	v_subrev_u32_e32 v209, 11, v196
	v_med3_i32 v209, v209, 0, v226
	v_lshl_add_u32 v209, v209, 2, v184
	ds_read_b32 v209, v209
	v_subrev_u32_e32 v210, 16, v196
	v_med3_i32 v210, v210, 0, v226
	v_lshl_add_u32 v210, v210, 2, v184
	ds_read_b32 v210, v210
	v_subrev_u32_e32 v211, 17, v196
	v_med3_i32 v211, v211, 0, v226
	v_lshl_add_u32 v211, v211, 2, v184
	ds_read_b32 v211, v211
	v_subrev_u32_e32 v212, 18, v196
	v_med3_i32 v212, v212, 0, v226
	v_lshl_add_u32 v212, v212, 2, v184
	ds_read_b32 v212, v212
	v_subrev_u32_e32 v213, 19, v196
	v_med3_i32 v213, v213, 0, v226
	v_lshl_add_u32 v213, v213, 2, v184
	ds_read_b32 v213, v213
	v_subrev_u32_e32 v80, 24, v196
	v_med3_i32 v80, v80, 0, v226
	v_lshl_add_u32 v80, v80, 2, v184
	ds_read_b32 v80, v80
	v_subrev_u32_e32 v81, 25, v196
	v_med3_i32 v81, v81, 0, v226
	v_lshl_add_u32 v81, v81, 2, v184
	ds_read_b32 v81, v81
	v_subrev_u32_e32 v82, 26, v196
	v_med3_i32 v82, v82, 0, v226
	v_lshl_add_u32 v82, v82, 2, v184
	ds_read_b32 v82, v82
	v_subrev_u32_e32 v83, 27, v196
	v_med3_i32 v83, v83, 0, v226
	v_lshl_add_u32 v83, v83, 2, v184
	ds_read_b32 v83, v83
	s_waitcnt lgkmcnt(0)
	s_nop 2
	v_add_f32_e32 v236, v236, v202
	v_add_f32_e32 v237, v237, v203
	v_add_f32_e32 v238, v238, v204
	v_add_f32_e32 v239, v239, v205
	v_add_f32_e32 v240, v240, v206
	v_add_f32_e32 v241, v241, v207
	v_add_f32_e32 v242, v242, v208
	v_add_f32_e32 v243, v243, v209
	v_add_f32_e32 v244, v244, v210
	v_add_f32_e32 v245, v245, v211
	v_add_f32_e32 v246, v246, v212
	v_add_f32_e32 v247, v247, v213
	v_add_f32_e32 v248, v248, v80
	v_add_f32_e32 v249, v249, v81
	v_add_f32_e32 v250, v250, v82
	v_add_f32_e32 v251, v251, v83
	v_mov_b32_e32 v200, 0
	s_branch .LdsaA_s0_msk

; __device__ __forceinline__ void dsa_attn_item(CParams& p, LAS unsigned char* lds, int b, int qb, int tid_in, int wave) {
;     ...
; #pragma unroll
;                 for (int i = 0; i < 16; ++i) { const int ko = (i & 3) + 8 * (i >> 2) + 4 * hh; const int dist = qp - (k0 + 32 * sub + ko);
;                     float bias = bfar; if (!far) bias = bdh[dist < 0 ? 0 : (dist < 128 ? dist : 128)];
;                     const float v = ((mw >> ko) & 1u) ? sc[i] + bias : -INFINITY; sc[i] = v; mx = fmaxf(mx, v); }
;                 mx = fmaxf(mx, __shfl_xor(mx, 32));
;                 const float m_new = fmaxf(m_run, mx);
;                 const float msafe = (m_new == -INFINITY) ? 0.f : m_new;
;                 const float alpha = __builtin_amdgcn_exp2f(m_run - msafe);
;                 const bool resc = __ballot(m_new > m_run) != 0ull;
;                 float ls = 0.f;
; #pragma unroll
;                 for (int i = 0; i < 16; ++i) { const float e = __builtin_amdgcn_exp2f(sc[i] - msafe); sc[i] = e; ls += e; }
;                 ls += __shfl_xor(ls, 32);
;                 l_run = l_run * alpha + ls; m_run = m_new;
.LdsaA_s0_msk:
	s_cmp_eq_u32 s100, 0
	s_cbranch_scc1 .LdsaA_s0_slow
	v_sub_f32_e32 v90, v201, v200

; #define LAS __attribute__((address_space(3)))
; __device__ __forceinline__ f32x16 mma32(const h16x8 a, const h16x8 b, const f32x16 c) { return __builtin_amdgcn_mfma_f32_32x32x16_f16(a, b, c, 0, 0, 0); }
; __device__ __forceinline__ void dsa_attn_item(CParams& p, LAS unsigned char* lds, int b, int qb, int tid_in, int wave) {
;     ...
; #pragma unroll
;             for (int sub = 0; sub < 2; ++sub) {
;                 const unsigned mw = (unsigned)(mk >> (32 * sub));
;                 if (__ballot(mw != 0u) == 0ull) continue;
;                 f32x16 sc;
; #pragma unroll
;                 for (int i = 0; i < 16; ++i) sc[i] = 0.f;
; #pragma unroll
;                 for (int s = 0; s < 8; ++s) sc = mma32(*(const LAS h16x8*)(Ks + (32 * sub + r) * 136 + 16 * s + 8 * hh), qf[s], sc);
;                 float mx = -INFINITY;
; #pragma unroll
;                 for (int i = 0; i < 16; ++i) { const int ko = (i & 3) + 8 * (i >> 2) + 4 * hh; const int dist = qp - (k0 + 32 * sub + ko);
;                     float bias = bfar; if (!far) bias = bdh[dist < 0 ? 0 : (dist < 128 ? dist : 128)];
;                     const float v = ((mw >> ko) & 1u) ? sc[i] + bias : -INFINITY; sc[i] = v; mx = fmaxf(mx, v); }
.LdsaA_s0_skip:
	s_mov_b32 s101, 0
.LdsaA_s1_top:
	v_lshrrev_b32_e32 v214, v146, v151
	v_bfe_u32 v227, v214, 0, 4
	v_lshl_add_u32 v227, v227, 4, s7
	ds_read_b128 v[236:239], v227
	v_bfe_u32 v227, v214, 8, 4
	v_lshl_add_u32 v227, v227, 4, s7
	ds_read_b128 v[240:243], v227
	v_bfe_u32 v227, v214, 16, 4
	v_lshl_add_u32 v227, v227, 4, s7
	ds_read_b128 v[244:247], v227
	v_bfe_u32 v227, v214, 24, 4
	v_lshl_add_u32 v227, v227, 4, s7
	ds_read_b128 v[248:251], v227
	ds_read_b128 v[80:83], v197 offset:8704
	ds_read_b128 v[84:87], v197 offset:8736
	ds_read_b128 v[88:91], v197 offset:8768
	ds_read_b128 v[92:95], v197 offset:8800
	ds_read_b128 v[202:205], v197 offset:8832
	ds_read_b128 v[206:209], v197 offset:8864
	ds_read_b128 v[210:213], v197 offset:8896
	ds_read_b128 v[228:231], v197 offset:8928
	s_waitcnt lgkmcnt(4)
	v_mfma_f32_32x32x16_f16 v[236:251], v[80:83], v[112:115], v[236:251]
	v_mfma_f32_32x32x16_f16 v[236:251], v[84:87], v[2:5], v[236:251]
	v_mfma_f32_32x32x16_f16 v[236:251], v[88:91], v[6:9], v[236:251]
	v_mfma_f32_32x32x16_f16 v[236:251], v[92:95], v[10:13], v[236:251]
	s_waitcnt lgkmcnt(0)
	v_mfma_f32_32x32x16_f16 v[236:251], v[202:205], v[96:99], v[236:251]
	v_mfma_f32_32x32x16_f16 v[236:251], v[206:209], v[100:103], v[236:251]
	v_mfma_f32_32x32x16_f16 v[236:251], v[210:213], v[104:107], v[236:251]
	v_mfma_f32_32x32x16_f16 v[236:251], v[228:231], v[108:111], v[236:251]
	s_cmp_le_i32 s31, s6
	s_cbranch_scc1 .LdsaA_s1_far
	v_subrev_u32_e32 v202, 32, v196
	v_med3_i32 v202, v202, 0, v226
	v_lshl_add_u32 v202, v202, 2, v184
	ds_read_b32 v202, v202
	v_subrev_u32_e32 v203, 33, v196
	v_med3_i32 v203, v203, 0, v226
	v_lshl_add_u32 v203, v203, 2, v184
	ds_read_b32 v203, v203
	v_subrev_u32_e32 v204, 34, v196
	v_med3_i32 v204, v204, 0, v226
	v_lshl_add_u32 v204, v204, 2, v184
	ds_read_b32 v204, v204
	v_subrev_u32_e32 v205, 35, v196
	v_med3_i32 v205, v205, 0, v226
	v_lshl_add_u32 v205, v205, 2, v184
	ds_read_b32 v205, v205
	v_subrev_u32_e32 v206, 40, v196
	v_med3_i32 v206, v206, 0, v226
	v_lshl_add_u32 v206, v206, 2, v184
	ds_read_b32 v206, v206
	v_subrev_u32_e32 v207, 41, v196
	v_med3_i32 v207, v207, 0, v226
	v_lshl_add_u32 v207, v207, 2, v184
	ds_read_b32 v207, v207
	v_subrev_u32_e32 v208, 42, v196
	v_med3_i32 v208, v208, 0, v226
	v_lshl_add_u32 v208, v208, 2, v184
	ds_read_b32 v208, v208
	v_subrev_u32_e32 v209, 43, v196
	v_med3_i32 v209, v209, 0, v226
	v_lshl_add_u32 v209, v209, 2, v184
	ds_read_b32 v209, v209
	v_subrev_u32_e32 v210, 48, v196
	v_med3_i32 v210, v210, 0, v226
	v_lshl_add_u32 v210, v210, 2, v184
	ds_read_b32 v210, v210
	v_subrev_u32_e32 v211, 49, v196
	v_med3_i32 v211, v211, 0, v226
	v_lshl_add_u32 v211, v211, 2, v184
	ds_read_b32 v211, v211
	v_subrev_u32_e32 v212, 50, v196
	v_med3_i32 v212, v212, 0, v226
	v_lshl_add_u32 v212, v212, 2, v184
	ds_read_b32 v212, v212
	v_subrev_u32_e32 v213, 51, v196
	v_med3_i32 v213, v213, 0, v226
	v_lshl_add_u32 v213, v213, 2, v184
	ds_read_b32 v213, v213
	v_subrev_u32_e32 v80, 56, v196
	v_med3_i32 v80, v80, 0, v226
	v_lshl_add_u32 v80, v80, 2, v184
	ds_read_b32 v80, v80
	v_subrev_u32_e32 v81, 57, v196
	v_med3_i32 v81, v81, 0, v226
	v_lshl_add_u32 v81, v81, 2, v184
	ds_read_b32 v81, v81
	v_subrev_u32_e32 v82, 58, v196
	v_med3_i32 v82, v82, 0, v226
	v_lshl_add_u32 v82, v82, 2, v184
	ds_read_b32 v82, v82
	v_subrev_u32_e32 v83, 59, v196
	v_med3_i32 v83, v83, 0, v226
	v_lshl_add_u32 v83, v83, 2, v184
	ds_read_b32 v83, v83
	s_waitcnt lgkmcnt(0)
	s_nop 2
	v_add_f32_e32 v236, v236, v202
	v_add_f32_e32 v237, v237, v203
	v_add_f32_e32 v238, v238, v204
	v_add_f32_e32 v239, v239, v205
	v_add_f32_e32 v240, v240, v206
	v_add_f32_e32 v241, v241, v207
	v_add_f32_e32 v242, v242, v208
	v_add_f32_e32 v243, v243, v209
	v_add_f32_e32 v244, v244, v210
	v_add_f32_e32 v245, v245, v211
	v_add_f32_e32 v246, v246, v212
	v_add_f32_e32 v247, v247, v213
	v_add_f32_e32 v248, v248, v80
	v_add_f32_e32 v249, v249, v81
	v_add_f32_e32 v250, v250, v82
	v_add_f32_e32 v251, v251, v83
	v_mov_b32_e32 v200, 0
	s_branch .LdsaA_s1_msk
